# speedup vs baseline: 1.0061x; 1.0061x over previous
; __device__ __forceinline__ float bf2f(u16 h) { return __uint_as_float(((unsigned)h) << 16); }
; __device__ __forceinline__ int tid_() { int t = threadIdx.x; asm volatile("" : "+v"(t)); return t; }
; __device__ __forceinline__ void phase_ain(const Params& P, int l, int bid, int nb) {
;   const int tidn = tid_();
;   const int wid = tidn >> 6, lane = tidn & 63;
;   const int c0 = lane * 16;
;   const float* og = P.onorm_g + (long)l * D;
;   for (int r = bid * 8 + wid; r < P.tg; r += nb * 8) {
;     float ov[16];
;     float ss = 0.f;
; #pragma unroll
;     for (int hh = 0; hh < 2; ++hh) {
;       u16x8 a = *(const u16x8*)(P.of + (long)r * D + c0 + hh * 8);
;       u16x8 a2 = *(const u16x8*)(P.h + (long)r * HS + c0 + hh * 8);
;       u16x8 b2 = *(const u16x8*)(P.h + (long)r * HS + 1024 + c0 + hh * 8);
; #pragma unroll
;       for (int e = 0; e < 8; ++e) { float v = bf2f(a[e]) + (bf2f(a2[e]) + bf2f(b2[e])); ov[hh * 8 + e] = v; ss += v * v; }
.LBB0_150:
	s_andn2_b64 vcc, exec, s[4:5]
	s_cbranch_vccnz .LBB0_407
	s_add_u32 s4, s2, 0x8400000
	s_addc_u32 s5, s3, 0
	s_add_u32 s94, s2, 0xe600000
	s_addc_u32 s95, s3, 0
	v_writelane_b32 v248, s42, 2
	s_add_u32 s70, s2, 0x41600000
	v_writelane_b32 v248, s4, 3
	s_addc_u32 s68, s3, 0
	s_and_b32 s46, 0xffff, s28
	v_writelane_b32 v248, s5, 4
	s_cmp_lt_i32 s46, 2
	s_mov_b64 s[4:5], -1
	s_cbranch_scc1 .LBB0_304
	s_cmp_gt_i32 s46, 2
	s_cbranch_scc0 .LBB0_157
	v_mov_b32_e32 v0, v182
	s_waitcnt vmcnt(0) lgkmcnt(0)
	v_ashrrev_i32_e32 v2, 6, v0
	s_waitcnt vmcnt(0)
	v_add_u32_e32 v36, s60, v2
	v_cmp_gt_i32_e32 vcc, s93, v36
	s_and_saveexec_b64 s[4:5], vcc
	v_readlane_b32 s10, v249, 15
	v_readlane_b32 s14, v249, 17
	v_readlane_b32 s11, v249, 16
	v_readlane_b32 s15, v249, 18
	s_mov_b32 s9, 0x800000
	s_mov_b32 s16, 0x8400000
	s_cbranch_execz .LBB0_156
	v_mov_b32_e32 v4, s45
	v_bfe_i32 v4, v4, 0, 8
	v_ashrrev_i32_e32 v5, 31, v4
	v_and_b32_e32 v3, 63, v0
	v_lshlrev_b64 v[4:5], 12, v[4:5]
	v_lshlrev_b32_e32 v0, 2, v3
	v_lshl_add_u64 v[4:5], s[76:77], 0, v[4:5]
	v_xor_b32_e32 v37, 32, v0
	v_xor_b32_e32 v38, 16, v0
	v_xor_b32_e32 v39, 8, v0
	v_xor_b32_e32 v40, 4, v0
	v_lshlrev_b32_e32 v0, 6, v3
	v_lshl_add_u64 v[18:19], v[4:5], 0, v[0:1]
	v_lshlrev_b32_e32 v0, 5, v3
	v_ashrrev_i32_e32 v3, 31, v2
	v_lshl_add_u64 v[2:3], s[60:61], 0, v[2:3]
	v_lshlrev_b64 v[4:5], 11, v[2:3]
	v_lshl_add_u64 v[20:21], s[2:3], 0, v[4:5]
	v_mov_b64_e32 v[4:5], s[2:3]
	v_mad_u64_u32 v[22:23], s[6:7], v2, s66, v[4:5]
	v_mad_i32_i24 v23, v3, s66, v23
	s_mov_b64 s[6:7], 0
	global_load_dwordx4 v[200:203], v[18:19], off offset:16
	global_load_dwordx4 v[204:207], v[18:19], off
	global_load_dwordx4 v[212:215], v[18:19], off offset:48
	global_load_dwordx4 v[216:219], v[18:19], off offset:32
.LBB0_155:
	v_lshl_add_u64 v[30:31], v[20:21], 0, v[0:1]
	v_add_co_u32_e32 v6, vcc, 0x30e00000, v30
	v_lshl_add_u64 v[34:35], v[22:23], 0, v[0:1]
	s_nop 0
	v_addc_co_u32_e32 v7, vcc, 0, v31, vcc
	v_add_co_u32_e32 v8, vcc, 0xe600000, v34
	global_load_dwordx4 v[2:5], v[6:7], off
	s_nop 0
	v_addc_co_u32_e32 v9, vcc, 0, v35, vcc
	global_load_dwordx4 v[26:29], v[8:9], off
	global_load_dwordx4 v[42:45], v[8:9], off offset:2048
	global_load_dwordx4 v[14:17], v[6:7], off offset:16
	global_load_dwordx4 v[10:13], v[8:9], off offset:16
	s_nop 0
	global_load_dwordx4 v[6:9], v[8:9], off offset:2064
	s_mov_b32 s8, 0xe601000
	v_add_co_u32_e32 v58, vcc, s8, v34
	v_add_u32_e32 v36, s62, v36
	s_nop 0
	v_addc_co_u32_e32 v59, vcc, 0, v35, vcc
	v_lshl_add_u64 v[20:21], v[20:21], 0, s[10:11]
	v_lshl_add_u64 v[22:23], v[22:23], 0, s[14:15]
	global_load_dwordx4 v[196:199], v[58:59], off
	global_load_dwordx4 v[208:211], v[58:59], off offset:16
	s_waitcnt vmcnt(0) lgkmcnt(0)
	v_and_b32_e32 v51, 0xffff0000, v26
	v_and_b32_e32 v35, 0xffff0000, v2
	v_lshlrev_b32_e32 v34, 16, v2
	v_and_b32_e32 v33, 0xffff0000, v13
	v_lshlrev_b32_e32 v32, 16, v13
	v_and_b32_e32 v47, 0xffff0000, v9
	v_lshlrev_b32_e32 v46, 16, v9
	v_pk_add_f32 v[32:33], v[32:33], v[46:47]
	v_mov_b64_e32 v[46:47], v[196:197]
	v_mov_b64_e32 v[48:49], v[198:199]
	v_lshlrev_b32_e32 v50, 16, v26
	v_lshlrev_b32_e32 v26, 16, v43
	v_and_b32_e32 v53, 0xffff0000, v42
	v_lshlrev_b32_e32 v52, 16, v42
	v_and_b32_e32 v67, 0xffff0000, v44
	v_lshlrev_b32_e32 v66, 16, v44
	v_pk_add_f32 v[50:51], v[50:51], v[52:53]
	v_and_b32_e32 v13, 0xffff0000, v12
	v_pk_add_f32 v[34:35], v[50:51], v[34:35]
	v_mov_b64_e32 v[50:51], v[200:201]
	v_mov_b64_e32 v[52:53], v[202:203]
	v_mov_b64_e32 v[54:55], v[204:205]
	v_mov_b64_e32 v[56:57], v[206:207]
	v_lshlrev_b32_e32 v12, 16, v12
	v_pk_mul_f32 v[60:61], v[34:35], v[34:35]
	v_and_b32_e32 v25, 0xffff0000, v17
	v_lshlrev_b32_e32 v24, 16, v17
	v_pk_add_f32 v[24:25], v[32:33], v[24:25]
	s_waitcnt vmcnt(0) lgkmcnt(0)
	v_lshlrev_b32_e32 v62, 16, v46
	v_mul_f32_e32 v2, 0xbfb8aa3b, v62
	v_exp_f32_e32 v2, v2
	v_and_b32_e32 v63, 0xffff0000, v46
	v_pk_mul_f32 v[32:33], v[24:25], v[24:25]
	v_add_f32_e32 v2, 1.0, v2
	v_rcp_f32_e32 v64, v2
	v_mul_f32_e32 v2, 0xbfb8aa3b, v63
	v_exp_f32_e32 v2, v2
	s_nop 0
	v_add_f32_e32 v2, 1.0, v2
	v_rcp_f32_e32 v65, v2
	v_lshlrev_b32_e32 v2, 16, v27
	v_pk_mul_f32 v[62:63], v[64:65], v[62:63]
	v_and_b32_e32 v65, 0xffff0000, v3
	v_lshlrev_b32_e32 v64, 16, v3
	v_and_b32_e32 v3, 0xffff0000, v27
	v_and_b32_e32 v27, 0xffff0000, v43
	v_pk_add_f32 v[2:3], v[2:3], v[26:27]
	s_nop 0
	v_pk_add_f32 v[42:43], v[2:3], v[64:65]
	v_lshlrev_b32_e32 v2, 16, v47
	v_mul_f32_e32 v9, 0xbfb8aa3b, v2
	v_exp_f32_e32 v9, v9
	v_and_b32_e32 v3, 0xffff0000, v47
	v_pk_mul_f32 v[64:65], v[42:43], v[42:43]
	v_add_f32_e32 v9, 1.0, v9
	v_rcp_f32_e32 v26, v9
	v_mul_f32_e32 v9, 0xbfb8aa3b, v3
	v_exp_f32_e32 v9, v9
	s_nop 0
	v_add_f32_e32 v9, 1.0, v9
	v_rcp_f32_e32 v27, v9
	v_and_b32_e32 v9, 0xffff0000, v8
	v_lshlrev_b32_e32 v8, 16, v8
	v_pk_add_f32 v[8:9], v[12:13], v[8:9]
	v_pk_mul_f32 v[46:47], v[26:27], v[2:3]
	v_and_b32_e32 v27, 0xffff0000, v28
	v_lshlrev_b32_e32 v26, 16, v28
	v_and_b32_e32 v3, 0xffff0000, v4
	v_lshlrev_b32_e32 v2, 16, v4
	v_pk_add_f32 v[26:27], v[26:27], v[66:67]
	v_lshlrev_b32_e32 v28, 16, v10
	v_pk_add_f32 v[66:67], v[26:27], v[2:3]
	v_lshlrev_b32_e32 v2, 16, v48
	v_mul_f32_e32 v4, 0xbfb8aa3b, v2
	v_exp_f32_e32 v4, v4
	v_and_b32_e32 v3, 0xffff0000, v48
	v_pk_mul_f32 v[68:69], v[66:67], v[66:67]
	v_add_f32_e32 v4, 1.0, v4
	v_rcp_f32_e32 v26, v4
	v_mul_f32_e32 v4, 0xbfb8aa3b, v3
	v_exp_f32_e32 v4, v4
	s_nop 0
	v_add_f32_e32 v4, 1.0, v4
	v_rcp_f32_e32 v27, v4
	v_lshlrev_b32_e32 v4, 16, v29
	v_pk_mul_f32 v[70:71], v[26:27], v[2:3]
	v_and_b32_e32 v3, 0xffff0000, v5
	v_lshlrev_b32_e32 v2, 16, v5
	v_and_b32_e32 v5, 0xffff0000, v29
	v_and_b32_e32 v27, 0xffff0000, v45
	v_lshlrev_b32_e32 v26, 16, v45
	v_pk_add_f32 v[4:5], v[4:5], v[26:27]
	v_and_b32_e32 v29, 0xffff0000, v10
	v_pk_add_f32 v[44:45], v[4:5], v[2:3]
	v_and_b32_e32 v3, 0xffff0000, v49
	v_lshlrev_b32_e32 v2, 16, v49
	v_mul_f32_e32 v4, 0xbfb8aa3b, v2
	v_mul_f32_e32 v5, 0xbfb8aa3b, v3
	v_exp_f32_e32 v4, v4
	v_exp_f32_e32 v5, v5
	v_and_b32_e32 v27, 0xffff0000, v14
	v_lshlrev_b32_e32 v26, 16, v14
	v_add_f32_e32 v4, 1.0, v4
	v_add_f32_e32 v5, 1.0, v5
	v_rcp_f32_e32 v4, v4
	v_rcp_f32_e32 v5, v5
	v_lshlrev_b32_e32 v14, 16, v11
	v_lshlrev_b32_e32 v10, 16, v7
	v_pk_mul_f32 v[72:73], v[44:45], v[44:45]
	v_pk_mul_f32 v[48:49], v[4:5], v[2:3]
	v_mov_b64_e32 v[2:3], v[208:209]
	v_mov_b64_e32 v[4:5], v[210:211]
	v_and_b32_e32 v59, 0xffff0000, v6
	v_lshlrev_b32_e32 v58, 16, v6
	v_pk_add_f32 v[28:29], v[28:29], v[58:59]
	s_nop 0
	v_pk_add_f32 v[26:27], v[28:29], v[26:27]
	s_waitcnt vmcnt(0) lgkmcnt(0)
; __device__ __forceinline__ float bf2f(u16 h) { return __uint_as_float(((unsigned)h) << 16); }
; __device__ __forceinline__ float siluf_(float x) { return x * __builtin_amdgcn_rcpf(1.0f + __expf(-x)); }
; __device__ __forceinline__ void phase_ain(const Params& P, int l, int bid, int nb) {
;     ...
;       for (int e = 0; e < 8; ++e) { float v = bf2f(a[e]) + (bf2f(a2[e]) + bf2f(b2[e])); ov[hh * 8 + e] = v; ss += v * v; }
;     }
; #pragma unroll
;     for (int o = 8; o >= 1; o >>= 1) ss += shfl_xor_l(ss, lane, o);
;     float rinv = rsqrtf(ss * (1.0f / 256.0f) + EPS);
; #pragma unroll
;     for (int hh = 0; hh < 2; ++hh) {
;       u16x8 rv = *(const u16x8*)(P.h + (long)r * HS + C_R + c0 + hh * 8);
;       u16x8 o;
; #pragma unroll
;       for (int e = 0; e < 8; ++e) o[e] = f2bf(ov[hh * 8 + e] * rinv * og[c0 + hh * 8 + e] * siluf_(bf2f(rv[e])));
;       *(u16x8*)(P.ain + (long)r * D + c0 + hh * 8) = o;
;     }
	v_lshlrev_b32_e32 v28, 16, v2
	v_and_b32_e32 v29, 0xffff0000, v2
	v_mul_f32_e32 v2, 0xbfb8aa3b, v28
	v_exp_f32_e32 v2, v2
	v_pk_mul_f32 v[58:59], v[26:27], v[26:27]
	v_add_f32_e32 v2, 1.0, v2
	v_rcp_f32_e32 v74, v2
	v_mul_f32_e32 v2, 0xbfb8aa3b, v29
	v_exp_f32_e32 v2, v2
	s_nop 0
	v_add_f32_e32 v2, 1.0, v2
	v_rcp_f32_e32 v75, v2
	s_nop 0
	v_pk_mul_f32 v[28:29], v[74:75], v[28:29]
	v_and_b32_e32 v75, 0xffff0000, v15
	v_lshlrev_b32_e32 v74, 16, v15
	v_and_b32_e32 v15, 0xffff0000, v11
	v_and_b32_e32 v11, 0xffff0000, v7
	v_pk_add_f32 v[6:7], v[14:15], v[10:11]
	v_and_b32_e32 v15, 0xffff0000, v3
	v_lshlrev_b32_e32 v14, 16, v3
	v_mul_f32_e32 v2, 0xbfb8aa3b, v14
	v_mul_f32_e32 v3, 0xbfb8aa3b, v15
	v_exp_f32_e32 v2, v2
	v_exp_f32_e32 v3, v3
	v_pk_add_f32 v[10:11], v[6:7], v[74:75]
	v_add_f32_e32 v2, 1.0, v2
	v_add_f32_e32 v3, 1.0, v3
	v_rcp_f32_e32 v2, v2
	v_rcp_f32_e32 v3, v3
	v_pk_mul_f32 v[6:7], v[10:11], v[10:11]
	v_pk_mul_f32 v[2:3], v[2:3], v[14:15]
	v_and_b32_e32 v15, 0xffff0000, v16
	v_lshlrev_b32_e32 v14, 16, v16
	v_pk_add_f32 v[12:13], v[8:9], v[14:15]
	v_add_f32_e32 v14, v60, v61
	v_add_f32_e32 v14, v64, v14
	v_add_f32_e32 v14, v65, v14
	v_add_f32_e32 v14, v68, v14
	v_add_f32_e32 v14, v69, v14
	v_add_f32_e32 v14, v72, v14
	v_add_f32_e32 v14, v73, v14
	v_add_f32_e32 v14, v58, v14
	v_add_f32_e32 v14, v59, v14
	v_add_f32_e32 v6, v6, v14
	v_pk_mul_f32 v[8:9], v[12:13], v[12:13]
	v_add_f32_e32 v6, v7, v6
	v_add_f32_e32 v6, v8, v6
	v_add_f32_e32 v6, v9, v6
	v_add_f32_e32 v6, v32, v6
	v_add_f32_e32 v6, v33, v6
	ds_bpermute_b32 v7, v37, v6
	s_waitcnt lgkmcnt(0)
	v_add_f32_e32 v6, v6, v7
	ds_bpermute_b32 v7, v38, v6
	s_waitcnt lgkmcnt(0)
	v_add_f32_e32 v6, v6, v7
	ds_bpermute_b32 v7, v39, v6
	s_waitcnt lgkmcnt(0)
	v_add_f32_e32 v6, v6, v7
	ds_bpermute_b32 v7, v40, v6
	s_waitcnt lgkmcnt(0)
	v_add_f32_e32 v6, v6, v7
	v_fmamk_f32 v6, v6, 0x3b800000, v183
	v_cmp_gt_f32_e32 vcc, s9, v6
	v_mul_f32_e32 v7, 0x4b800000, v6
	s_nop 0
	v_cndmask_b32_e32 v6, v6, v7, vcc
	v_rsq_f32_e32 v6, v6
	s_nop 0
	v_mul_f32_e32 v7, 0x45800000, v6
	v_cndmask_b32_e32 v14, v6, v7, vcc
	v_pk_mul_f32 v[6:7], v[34:35], v[14:15] op_sel_hi:[1,0]
	v_pk_mul_f32 v[8:9], v[42:43], v[14:15] op_sel_hi:[1,0]
	v_pk_mul_f32 v[6:7], v[54:55], v[6:7]
	v_pk_mul_f32 v[8:9], v[56:57], v[8:9]
	v_pk_mul_f32 v[6:7], v[62:63], v[6:7]
	v_pk_mul_f32 v[8:9], v[46:47], v[8:9]
	v_cvt_pk_bf16_f32 v6, v6, v7
	v_cvt_pk_bf16_f32 v7, v8, v9
	v_pk_mul_f32 v[8:9], v[66:67], v[14:15] op_sel_hi:[1,0]
	v_pk_mul_f32 v[16:17], v[44:45], v[14:15] op_sel_hi:[1,0]
	v_pk_mul_f32 v[8:9], v[50:51], v[8:9]
	v_pk_mul_f32 v[16:17], v[52:53], v[16:17]
	v_pk_mul_f32 v[8:9], v[70:71], v[8:9]
	v_pk_mul_f32 v[16:17], v[48:49], v[16:17]
	v_cvt_pk_bf16_f32 v8, v8, v9
	v_cvt_pk_bf16_f32 v9, v16, v17
	v_add_co_u32_e32 v16, vcc, s16, v30
	v_pk_mul_f32 v[26:27], v[26:27], v[14:15] op_sel_hi:[1,0]
	s_nop 0
	v_addc_co_u32_e32 v17, vcc, 0, v31, vcc
	global_store_dwordx4 v[16:17], v[6:9], off offset:2048
	s_nop 1
	v_mov_b64_e32 v[6:7], v[212:213]
	v_mov_b64_e32 v[8:9], v[214:215]
	s_nop 0
	v_mov_b64_e32 v[30:31], v[216:217]
	v_mov_b64_e32 v[32:33], v[218:219]
	v_pk_mul_f32 v[10:11], v[10:11], v[14:15] op_sel_hi:[1,0]
	v_pk_mul_f32 v[12:13], v[12:13], v[14:15] op_sel_hi:[1,0]
	v_cmp_le_i32_e32 vcc, s93, v36
	s_or_b64 s[6:7], vcc, s[6:7]
	s_nop 0
	v_pk_mul_f32 v[6:7], v[6:7], v[12:13]
	v_pk_mul_f32 v[26:27], v[30:31], v[26:27]
	v_pk_mul_f32 v[10:11], v[32:33], v[10:11]
	v_pk_mul_f32 v[26:27], v[28:29], v[26:27]
	v_pk_mul_f32 v[2:3], v[2:3], v[10:11]
	v_cvt_pk_bf16_f32 v26, v26, v27
	v_cvt_pk_bf16_f32 v27, v2, v3
	v_lshlrev_b32_e32 v2, 16, v4
	v_and_b32_e32 v3, 0xffff0000, v4
	v_mul_f32_e32 v4, 0xbfb8aa3b, v2
	v_exp_f32_e32 v4, v4
	s_nop 0
	v_add_f32_e32 v4, 1.0, v4
	v_rcp_f32_e32 v10, v4
	v_mul_f32_e32 v4, 0xbfb8aa3b, v3
	v_exp_f32_e32 v4, v4
	s_nop 0
	v_add_f32_e32 v4, 1.0, v4
	v_rcp_f32_e32 v11, v4
	s_nop 0
	v_pk_mul_f32 v[2:3], v[10:11], v[2:3]
	s_nop 0
	v_pk_mul_f32 v[2:3], v[2:3], v[6:7]
	v_pk_mul_f32 v[6:7], v[24:25], v[14:15] op_sel_hi:[1,0]
	v_cvt_pk_bf16_f32 v28, v2, v3
	v_and_b32_e32 v3, 0xffff0000, v5
	v_lshlrev_b32_e32 v2, 16, v5
	v_mul_f32_e32 v4, 0xbfb8aa3b, v2
	v_mul_f32_e32 v5, 0xbfb8aa3b, v3
	v_exp_f32_e32 v4, v4
	v_exp_f32_e32 v5, v5
	v_pk_mul_f32 v[6:7], v[8:9], v[6:7]
	v_add_f32_e32 v4, 1.0, v4
	v_add_f32_e32 v5, 1.0, v5
	v_rcp_f32_e32 v4, v4
	v_rcp_f32_e32 v5, v5
	s_nop 0
	v_pk_mul_f32 v[2:3], v[4:5], v[2:3]
	s_nop 0
	v_pk_mul_f32 v[2:3], v[2:3], v[6:7]
	s_nop 0
	v_cvt_pk_bf16_f32 v29, v2, v3
	global_store_dwordx4 v[16:17], v[26:29], off offset:2064
	s_andn2_b64 exec, exec, s[6:7]
	s_cbranch_execnz .LBB0_155
